# attention: deferred PV + packed f32 row-sum adds (v_pk_add_f32) on top of v22
# baseline (speedup 1.0000x reference)
; __device__ __forceinline__ unsigned cvt_pk_bf16(float lo, float hi) { unsigned r; asm volatile("v_cvt_pk_bf16_f32 %0, %1, %2" : "=v"(r) : "v"(lo), "v"(hi)); return r; }
; __device__ __forceinline__ void phase_attn(const Params& p, unsigned char* lds) {
;     ...
;             float mloc = st[0][0];
; #pragma unroll
;             for (int i = 0; i < 16; ++i) { mloc = fmaxf(mloc, st[0][i]); mloc = fmaxf(mloc, st[1][i]); }
;             mloc = fmaxf(mloc, __shfl_xor(mloc, 32));
;             const float mnew = fmaxf(mrun, mloc);
;             if (__builtin_amdgcn_ballot_w64(mnew > mrun) != 0ull) {
;                 const float alpha = __builtin_amdgcn_exp2f(mrun - mnew);
;                 lsum *= alpha;
; #pragma unroll
;                 for (int vb = 0; vb < 4; ++vb)
; #pragma unroll
;                     for (int i = 0; i < 16; ++i) ot[vb][i] *= alpha;
;             }
;             mrun = mnew;
;             bf16x8 P[2][2];
; #pragma unroll
;             for (int kb = 0; kb < 2; ++kb)
; #pragma unroll
;                 for (int s2 = 0; s2 < 2; ++s2) { u32x4 pk;
; #pragma unroll
;                     for (int jj = 0; jj < 4; ++jj) { const float p0 = __builtin_amdgcn_exp2f(st[kb][8 * s2 + 2 * jj] - mnew), p1 = __builtin_amdgcn_exp2f(st[kb][8 * s2 + 2 * jj + 1] - mnew); lsum += p0 + p1; pk[jj] = cvt_pk_bf16(p0, p1); }
;                     P[kb][s2] = __builtin_bit_cast(bf16x8, pk); }
;             {
;                 bf16x8 vf[2][4];
;     ...
;                 AT_LDV(0, 0);
; #pragma unroll
;                 for (int vb = 0; vb < 4; ++vb) {
;                     if (vb < 3) AT_LDV((vb + 1) & 1, vb + 1);
;                     __builtin_amdgcn_sched_barrier(0);
;                     __builtin_amdgcn_s_setprio(2);
; #pragma unroll
;                     for (int kb = 0; kb < 2; ++kb)
; #pragma unroll
;                         for (int s2 = 0; s2 < 2; ++s2) ot[vb] = __builtin_amdgcn_mfma_f32_32x32x16_bf16(vf[vb & 1][kb * 2 + s2], P[kb][s2], ot[vb], 0, 0, 0);
;                     __builtin_amdgcn_s_setprio(0);
;                     __builtin_amdgcn_sched_barrier(0);
;                 }
;     ...
;             }
;             if (kt + 1 < 64) { AT_STOREK(buf ^ 1); AT_STOREV(buf ^ 1); }
.Lat_norescale_1:
	v_mov_b32_e32 v236, 0
	v_mov_b32_e32 v237, 0
	s_waitcnt lgkmcnt(7)
	v_mfma_f32_32x32x16_bf16 v[196:211], v[172:175], v[108:111], 0
	v_sub_f32_e32 v80, v80, v149
	v_sub_f32_e32 v81, v81, v149
	v_sub_f32_e32 v82, v82, v149
	v_sub_f32_e32 v83, v83, v149
	v_exp_f32_e32 v80, v80
	v_exp_f32_e32 v81, v81
	v_exp_f32_e32 v82, v82
	v_exp_f32_e32 v83, v83
	v_pk_add_f32 v[236:237], v[236:237], v[80:81]
	v_cvt_pk_bf16_f32 v80, v80, v81
	v_pk_add_f32 v[236:237], v[236:237], v[82:83]
	v_cvt_pk_bf16_f32 v81, v82, v83
	s_waitcnt lgkmcnt(6)
	v_mfma_f32_32x32x16_bf16 v[196:211], v[176:179], v[104:107], v[196:211]
	v_sub_f32_e32 v84, v84, v149
	v_sub_f32_e32 v85, v85, v149
	v_sub_f32_e32 v86, v86, v149
	v_sub_f32_e32 v87, v87, v149
	v_exp_f32_e32 v84, v84
	v_exp_f32_e32 v85, v85
	v_exp_f32_e32 v86, v86
	v_exp_f32_e32 v87, v87
	v_pk_add_f32 v[236:237], v[236:237], v[84:85]
	v_cvt_pk_bf16_f32 v82, v84, v85
	v_pk_add_f32 v[236:237], v[236:237], v[86:87]
	v_cvt_pk_bf16_f32 v83, v86, v87
	s_waitcnt lgkmcnt(5)
	v_mfma_f32_32x32x16_bf16 v[196:211], v[180:183], v[100:103], v[196:211]
	v_sub_f32_e32 v88, v88, v149
	v_sub_f32_e32 v89, v89, v149
	v_sub_f32_e32 v90, v90, v149
	v_sub_f32_e32 v91, v91, v149
	v_exp_f32_e32 v88, v88
	v_exp_f32_e32 v89, v89
	v_exp_f32_e32 v90, v90
	v_exp_f32_e32 v91, v91
	v_pk_add_f32 v[236:237], v[236:237], v[88:89]
	v_cvt_pk_bf16_f32 v84, v88, v89
	v_pk_add_f32 v[236:237], v[236:237], v[90:91]
	v_cvt_pk_bf16_f32 v85, v90, v91
	s_waitcnt lgkmcnt(4)
	v_mfma_f32_32x32x16_bf16 v[196:211], v[184:187], v[96:99], v[196:211]
	ds_read_b128 v[172:175], v159 offset:34816
	ds_read_b128 v[176:179], v159 offset:34848
	ds_read_b128 v[180:183], v159 offset:34880
	ds_read_b128 v[184:187], v159 offset:34912
	v_sub_f32_e32 v92, v92, v149
	v_sub_f32_e32 v93, v93, v149
	v_sub_f32_e32 v94, v94, v149
	v_sub_f32_e32 v95, v95, v149
	v_exp_f32_e32 v92, v92
	v_exp_f32_e32 v93, v93
	v_exp_f32_e32 v94, v94
	v_exp_f32_e32 v95, v95
	v_pk_add_f32 v[236:237], v[236:237], v[92:93]
	v_cvt_pk_bf16_f32 v86, v92, v93
	v_pk_add_f32 v[236:237], v[236:237], v[94:95]
	v_cvt_pk_bf16_f32 v87, v94, v95
	s_waitcnt lgkmcnt(7)
	v_mfma_f32_32x32x16_bf16 v[212:227], v[188:191], v[108:111], 0
	v_sub_f32_e32 v64, v64, v149
	v_sub_f32_e32 v65, v65, v149
	v_sub_f32_e32 v66, v66, v149
	v_sub_f32_e32 v67, v67, v149
	v_exp_f32_e32 v64, v64
	v_exp_f32_e32 v65, v65
	v_exp_f32_e32 v66, v66
	v_exp_f32_e32 v67, v67
	v_pk_add_f32 v[236:237], v[236:237], v[64:65]
	v_cvt_pk_bf16_f32 v64, v64, v65
	v_pk_add_f32 v[236:237], v[236:237], v[66:67]
	v_cvt_pk_bf16_f32 v65, v66, v67
	s_waitcnt lgkmcnt(6)
	v_mfma_f32_32x32x16_bf16 v[212:227], v[192:195], v[104:107], v[212:227]
	v_sub_f32_e32 v68, v68, v149
	v_sub_f32_e32 v69, v69, v149
	v_sub_f32_e32 v70, v70, v149
	v_sub_f32_e32 v71, v71, v149
	v_exp_f32_e32 v68, v68
	v_exp_f32_e32 v69, v69
	v_exp_f32_e32 v70, v70
	v_exp_f32_e32 v71, v71
	v_pk_add_f32 v[236:237], v[236:237], v[68:69]
	v_cvt_pk_bf16_f32 v66, v68, v69
	v_pk_add_f32 v[236:237], v[236:237], v[70:71]
	v_cvt_pk_bf16_f32 v67, v70, v71
	s_waitcnt lgkmcnt(5)
	v_mfma_f32_32x32x16_bf16 v[212:227], v[228:231], v[100:103], v[212:227]
	v_sub_f32_e32 v72, v72, v149
	v_sub_f32_e32 v73, v73, v149
	v_sub_f32_e32 v74, v74, v149
	v_sub_f32_e32 v75, v75, v149
	v_exp_f32_e32 v72, v72
	v_exp_f32_e32 v73, v73
	v_exp_f32_e32 v74, v74
	v_exp_f32_e32 v75, v75
	v_pk_add_f32 v[236:237], v[236:237], v[72:73]
	v_cvt_pk_bf16_f32 v68, v72, v73
	v_pk_add_f32 v[236:237], v[236:237], v[74:75]
	v_cvt_pk_bf16_f32 v69, v74, v75
	s_waitcnt lgkmcnt(4)
	v_mfma_f32_32x32x16_bf16 v[212:227], v[232:235], v[96:99], v[212:227]
	ds_read_b128 v[188:191], v159 offset:39424
	ds_read_b128 v[192:195], v159 offset:39456
	ds_read_b128 v[228:231], v159 offset:39488
	ds_read_b128 v[232:235], v159 offset:39520
	v_sub_f32_e32 v76, v76, v149
	v_sub_f32_e32 v77, v77, v149
	v_sub_f32_e32 v78, v78, v149
	v_sub_f32_e32 v79, v79, v149
	v_exp_f32_e32 v76, v76
	v_exp_f32_e32 v77, v77
	v_exp_f32_e32 v78, v78
	v_exp_f32_e32 v79, v79
	v_pk_add_f32 v[236:237], v[236:237], v[76:77]
	v_cvt_pk_bf16_f32 v70, v76, v77
	v_pk_add_f32 v[236:237], v[236:237], v[78:79]
	v_cvt_pk_bf16_f32 v71, v78, v79
	v_add_f32_e32 v128, v128, v236
	v_add_f32_e32 v128, v128, v237
	s_waitcnt lgkmcnt(7)
	v_mfma_f32_32x32x16_bf16 v[48:63], v[172:175], v[80:83], v[48:63]
	s_waitcnt lgkmcnt(6)
	v_mfma_f32_32x32x16_bf16 v[48:63], v[176:179], v[84:87], v[48:63]
	v_max3_f32 v145, v196, v197, v198
	v_max3_f32 v237, v212, v213, v214
	v_max3_f32 v145, v145, v199, v200
	s_waitcnt lgkmcnt(5)
	v_mfma_f32_32x32x16_bf16 v[48:63], v[180:183], v[64:67], v[48:63]
	v_max3_f32 v237, v237, v215, v216
	v_max3_f32 v145, v145, v201, v202
	v_max3_f32 v237, v237, v217, v218
	s_waitcnt lgkmcnt(4)
	v_mfma_f32_32x32x16_bf16 v[48:63], v[184:187], v[68:71], v[48:63]
	v_max3_f32 v145, v145, v203, v204
	v_max3_f32 v237, v237, v219, v220
	v_max3_f32 v145, v145, v205, v206
	ds_read_b128 v[172:175], v159 offset:44032
	ds_read_b128 v[176:179], v159 offset:44064
	ds_read_b128 v[180:183], v159 offset:44096
	ds_read_b128 v[184:187], v159 offset:44128
	s_waitcnt lgkmcnt(7)
	v_mfma_f32_32x32x16_bf16 v[32:47], v[188:191], v[80:83], v[32:47]
	v_max3_f32 v237, v237, v221, v222
	v_max3_f32 v145, v145, v207, v208
	v_max3_f32 v237, v237, v223, v224
	s_waitcnt lgkmcnt(6)
	v_mfma_f32_32x32x16_bf16 v[32:47], v[192:195], v[84:87], v[32:47]
	v_max3_f32 v145, v145, v209, v210
	v_max3_f32 v237, v237, v225, v226
	v_max_f32_e32 v145, v145, v211
	s_waitcnt lgkmcnt(5)
	v_mfma_f32_32x32x16_bf16 v[32:47], v[228:231], v[64:67], v[32:47]
	v_max_f32_e32 v237, v237, v227
	v_max_f32_e32 v145, v145, v237
	ds_bpermute_b32 v237, v158, v145
	s_waitcnt lgkmcnt(5)
	v_mfma_f32_32x32x16_bf16 v[32:47], v[232:235], v[68:71], v[32:47]
	v_add_u32_e32 v239, v131, v164
	s_waitcnt vmcnt(3)
	ds_write_b128 v239, v[116:119] offset:0
	ds_read_b128 v[188:191], v159 offset:48640
	ds_read_b128 v[192:195], v159 offset:48672
	ds_read_b128 v[228:231], v159 offset:48704
	ds_read_b128 v[232:235], v159 offset:48736
	s_waitcnt lgkmcnt(9)
	v_mfma_f32_32x32x16_bf16 v[16:31], v[172:175], v[80:83], v[16:31]
	v_add_u32_e32 v239, v131, v165
	s_waitcnt vmcnt(2)
	ds_write_b128 v239, v[112:115] offset:0
	s_waitcnt lgkmcnt(9)
	v_mfma_f32_32x32x16_bf16 v[16:31], v[176:179], v[84:87], v[16:31]
	v_add_u32_e32 v239, v156, v166
	s_waitcnt vmcnt(1)
	ds_write_b128 v239, v[124:127] offset:53248
	s_waitcnt lgkmcnt(9)
	v_mfma_f32_32x32x16_bf16 v[16:31], v[180:183], v[64:67], v[16:31]
	v_add_u32_e32 v239, v156, v167
	s_waitcnt vmcnt(0)
	ds_write_b128 v239, v[120:123] offset:53248
	s_waitcnt lgkmcnt(9)
	v_mfma_f32_32x32x16_bf16 v[16:31], v[184:187], v[68:71], v[16:31]
	s_waitcnt lgkmcnt(8)
	v_max_f32_e32 v237, v145, v237
	v_add_f32_e32 v239, 0x41000000, v149
	v_max_f32_e32 v145, v149, v237
	v_sub_f32_e32 v238, v149, v145
	v_cmp_gt_f32_e32 vcc, v237, v239
	v_exp_f32_e32 v238, v238
	s_cbranch_vccz .Lat_keepm_2
	v_mov_b32_e32 v149, v145

; __device__ __forceinline__ unsigned cvt_pk_bf16(float lo, float hi) { unsigned r; asm volatile("v_cvt_pk_bf16_f32 %0, %1, %2" : "=v"(r) : "v"(lo), "v"(hi)); return r; }
; #define AT_LDV(set, vb) do { _Pragma("unroll") for (int kb = 0; kb < 2; ++kb) _Pragma("unroll") for (int s2 = 0; s2 < 2; ++s2) \
;                     vf[set][kb * 2 + s2] = *(const bf16x8*)(sVt + buf * 9216 + (32 * (vb) + ql) * 72 + 32 * kb + 16 * s2 + 8 * g); } while (0)
; __device__ __forceinline__ void phase_attn(const Params& p, unsigned char* lds) {
;     ...
;             AT_QK(st, buf);
;             float mloc = st[0][0];
; #pragma unroll
;             for (int i = 0; i < 16; ++i) { mloc = fmaxf(mloc, st[0][i]); mloc = fmaxf(mloc, st[1][i]); }
;             mloc = fmaxf(mloc, __shfl_xor(mloc, 32));
;             const float mnew = fmaxf(mrun, mloc);
;             if (__builtin_amdgcn_ballot_w64(mnew > mrun) != 0ull) {
;                 const float alpha = __builtin_amdgcn_exp2f(mrun - mnew);
;                 lsum *= alpha;
; #pragma unroll
;                 for (int vb = 0; vb < 4; ++vb)
; #pragma unroll
;                     for (int i = 0; i < 16; ++i) ot[vb][i] *= alpha;
;             }
;             mrun = mnew;
;             bf16x8 P[2][2];
; #pragma unroll
;             for (int kb = 0; kb < 2; ++kb)
; #pragma unroll
;                 for (int s2 = 0; s2 < 2; ++s2) { u32x4 pk;
; #pragma unroll
;                     for (int jj = 0; jj < 4; ++jj) { const float p0 = __builtin_amdgcn_exp2f(st[kb][8 * s2 + 2 * jj] - mnew), p1 = __builtin_amdgcn_exp2f(st[kb][8 * s2 + 2 * jj + 1] - mnew); lsum += p0 + p1; pk[jj] = cvt_pk_bf16(p0, p1); }
;                     P[kb][s2] = __builtin_bit_cast(bf16x8, pk); }
;             {
;                 bf16x8 vf[2][4];
;     ...
;                 AT_LDV(0, 0);
; #pragma unroll
;                 for (int vb = 0; vb < 4; ++vb) {
;                     if (vb < 3) AT_LDV((vb + 1) & 1, vb + 1);
;                     __builtin_amdgcn_sched_barrier(0);
;                     __builtin_amdgcn_s_setprio(2);
; #pragma unroll
;                     for (int kb = 0; kb < 2; ++kb)
; #pragma unroll
;                         for (int s2 = 0; s2 < 2; ++s2) ot[vb] = __builtin_amdgcn_mfma_f32_32x32x16_bf16(vf[vb & 1][kb * 2 + s2], P[kb][s2], ot[vb], 0, 0, 0);
.Lat_norescale_3:
	v_mov_b32_e32 v236, 0
	v_mov_b32_e32 v237, 0
	v_mfma_f32_32x32x16_bf16 v[0:15], v[188:191], v[80:83], v[0:15]
	v_sub_f32_e32 v196, v196, v149
	v_sub_f32_e32 v197, v197, v149
	v_sub_f32_e32 v198, v198, v149
	v_sub_f32_e32 v199, v199, v149
	v_exp_f32_e32 v196, v196
	v_exp_f32_e32 v197, v197
	v_exp_f32_e32 v198, v198
	v_exp_f32_e32 v199, v199
	v_pk_add_f32 v[236:237], v[236:237], v[196:197]
	v_cvt_pk_bf16_f32 v196, v196, v197
	v_pk_add_f32 v[236:237], v[236:237], v[198:199]
	v_cvt_pk_bf16_f32 v197, v198, v199
	v_mfma_f32_32x32x16_bf16 v[0:15], v[192:195], v[84:87], v[0:15]
	v_sub_f32_e32 v200, v200, v149
	v_sub_f32_e32 v201, v201, v149
	v_sub_f32_e32 v202, v202, v149
	v_sub_f32_e32 v203, v203, v149
	v_exp_f32_e32 v200, v200
	v_exp_f32_e32 v201, v201
	v_exp_f32_e32 v202, v202
	v_exp_f32_e32 v203, v203
	v_pk_add_f32 v[236:237], v[236:237], v[200:201]
	v_cvt_pk_bf16_f32 v198, v200, v201
	v_pk_add_f32 v[236:237], v[236:237], v[202:203]
	v_cvt_pk_bf16_f32 v199, v202, v203
	v_mfma_f32_32x32x16_bf16 v[0:15], v[228:231], v[64:67], v[0:15]
	v_sub_f32_e32 v204, v204, v149
	v_sub_f32_e32 v205, v205, v149
	v_sub_f32_e32 v206, v206, v149
	v_sub_f32_e32 v207, v207, v149
	v_exp_f32_e32 v204, v204
	v_exp_f32_e32 v205, v205
	v_exp_f32_e32 v206, v206
	v_exp_f32_e32 v207, v207
	v_pk_add_f32 v[236:237], v[236:237], v[204:205]
	v_cvt_pk_bf16_f32 v200, v204, v205
	v_pk_add_f32 v[236:237], v[236:237], v[206:207]
	v_cvt_pk_bf16_f32 v201, v206, v207
	v_mfma_f32_32x32x16_bf16 v[0:15], v[232:235], v[68:71], v[0:15]
	ds_read_b128 v[188:191], v157 offset:8704
	ds_read_b128 v[192:195], v157 offset:8736
	ds_read_b128 v[228:231], v157 offset:8768
	ds_read_b128 v[232:235], v157 offset:8800
	v_sub_f32_e32 v208, v208, v149
	v_sub_f32_e32 v209, v209, v149
	v_sub_f32_e32 v210, v210, v149
	v_sub_f32_e32 v211, v211, v149
	v_exp_f32_e32 v208, v208
	v_exp_f32_e32 v209, v209
	v_exp_f32_e32 v210, v210
	v_exp_f32_e32 v211, v211
	v_pk_add_f32 v[236:237], v[236:237], v[208:209]
	v_cvt_pk_bf16_f32 v202, v208, v209
	v_pk_add_f32 v[236:237], v[236:237], v[210:211]
	v_cvt_pk_bf16_f32 v203, v210, v211
	s_waitcnt lgkmcnt(7)
	v_mfma_f32_32x32x16_bf16 v[80:95], v[172:175], v[108:111], 0
	v_sub_f32_e32 v212, v212, v149
	v_sub_f32_e32 v213, v213, v149
	v_exp_f32_e32 v212, v212
	v_exp_f32_e32 v213, v213
	s_nop 0
	v_pk_add_f32 v[236:237], v[236:237], v[212:213]
	v_cvt_pk_bf16_f32 v212, v212, v213
	s_waitcnt lgkmcnt(6)
	v_mfma_f32_32x32x16_bf16 v[80:95], v[176:179], v[104:107], v[80:95]
	v_sub_f32_e32 v214, v214, v149
	v_sub_f32_e32 v215, v215, v149
	v_exp_f32_e32 v214, v214
	v_exp_f32_e32 v215, v215
	s_nop 0
	v_pk_add_f32 v[236:237], v[236:237], v[214:215]
	v_cvt_pk_bf16_f32 v213, v214, v215
	s_cbranch_vccz .Lat_norescale_4
	v_pk_mul_f32 v[14:15], v[14:15], v[238:239] op_sel_hi:[1,0]
	v_pk_mul_f32 v[12:13], v[12:13], v[238:239] op_sel_hi:[1,0]
	v_pk_mul_f32 v[10:11], v[10:11], v[238:239] op_sel_hi:[1,0]
	v_pk_mul_f32 v[8:9], v[8:9], v[238:239] op_sel_hi:[1,0]
	v_pk_mul_f32 v[6:7], v[6:7], v[238:239] op_sel_hi:[1,0]
	v_pk_mul_f32 v[4:5], v[4:5], v[238:239] op_sel_hi:[1,0]
	v_pk_mul_f32 v[2:3], v[2:3], v[238:239] op_sel_hi:[1,0]
	v_pk_mul_f32 v[0:1], v[0:1], v[238:239] op_sel_hi:[1,0]
; __device__ __forceinline__ unsigned cvt_pk_bf16(float lo, float hi) { unsigned r; asm volatile("v_cvt_pk_bf16_f32 %0, %1, %2" : "=v"(r) : "v"(lo), "v"(hi)); return r; }
; __device__ __forceinline__ void phase_attn(const Params& p, unsigned char* lds) {
;     ...
;             AT_QK(st, buf);
;             float mloc = st[0][0];
; #pragma unroll
;             for (int i = 0; i < 16; ++i) { mloc = fmaxf(mloc, st[0][i]); mloc = fmaxf(mloc, st[1][i]); }
;             mloc = fmaxf(mloc, __shfl_xor(mloc, 32));
;             const float mnew = fmaxf(mrun, mloc);
;             if (__builtin_amdgcn_ballot_w64(mnew > mrun) != 0ull) {
;                 const float alpha = __builtin_amdgcn_exp2f(mrun - mnew);
;                 lsum *= alpha;
; #pragma unroll
;                 for (int vb = 0; vb < 4; ++vb)
; #pragma unroll
;                     for (int i = 0; i < 16; ++i) ot[vb][i] *= alpha;
;             }
;             mrun = mnew;
;             bf16x8 P[2][2];
; #pragma unroll
;             for (int kb = 0; kb < 2; ++kb)
; #pragma unroll
;                 for (int s2 = 0; s2 < 2; ++s2) { u32x4 pk;
; #pragma unroll
;                     for (int jj = 0; jj < 4; ++jj) { const float p0 = __builtin_amdgcn_exp2f(st[kb][8 * s2 + 2 * jj] - mnew), p1 = __builtin_amdgcn_exp2f(st[kb][8 * s2 + 2 * jj + 1] - mnew); lsum += p0 + p1; pk[jj] = cvt_pk_bf16(p0, p1); }
;                     P[kb][s2] = __builtin_bit_cast(bf16x8, pk); }
;             {
;                 bf16x8 vf[2][4];
;     ...
;                 AT_LDV(0, 0);
; #pragma unroll
;                 for (int vb = 0; vb < 4; ++vb) {
;                     if (vb < 3) AT_LDV((vb + 1) & 1, vb + 1);
;                     __builtin_amdgcn_sched_barrier(0);
;                     __builtin_amdgcn_s_setprio(2);
; #pragma unroll
;                     for (int kb = 0; kb < 2; ++kb)
; #pragma unroll
;                         for (int s2 = 0; s2 < 2; ++s2) ot[vb] = __builtin_amdgcn_mfma_f32_32x32x16_bf16(vf[vb & 1][kb * 2 + s2], P[kb][s2], ot[vb], 0, 0, 0);
;                     __builtin_amdgcn_s_setprio(0);
;                     __builtin_amdgcn_sched_barrier(0);
;                 }
;     ...
;             }
;             if (kt + 1 < 64) { AT_STOREK(buf ^ 1); AT_STOREV(buf ^ 1); }
;             __syncthreads();
;         }
.Lat_norescale_4:
	s_waitcnt lgkmcnt(5)
	v_mfma_f32_32x32x16_bf16 v[80:95], v[180:183], v[100:103], v[80:95]
	v_sub_f32_e32 v216, v216, v149
	v_sub_f32_e32 v217, v217, v149
	v_exp_f32_e32 v216, v216
	v_exp_f32_e32 v217, v217
	s_nop 0
	v_pk_add_f32 v[236:237], v[236:237], v[216:217]
	v_cvt_pk_bf16_f32 v214, v216, v217
	s_waitcnt lgkmcnt(4)
	v_mfma_f32_32x32x16_bf16 v[80:95], v[184:187], v[96:99], v[80:95]
	ds_read_b128 v[172:175], v147 offset:34816
	ds_read_b128 v[176:179], v147 offset:34848
	ds_read_b128 v[180:183], v147 offset:34880
	ds_read_b128 v[184:187], v147 offset:34912
	v_sub_f32_e32 v218, v218, v149
	v_sub_f32_e32 v219, v219, v149
	v_exp_f32_e32 v218, v218
	v_exp_f32_e32 v219, v219
	s_nop 0
	v_pk_add_f32 v[236:237], v[236:237], v[218:219]
	v_cvt_pk_bf16_f32 v215, v218, v219
	s_waitcnt lgkmcnt(7)
	v_mfma_f32_32x32x16_bf16 v[64:79], v[188:191], v[108:111], 0
	v_sub_f32_e32 v220, v220, v149
	v_sub_f32_e32 v221, v221, v149
	v_exp_f32_e32 v220, v220
	v_exp_f32_e32 v221, v221
	s_nop 0
	v_pk_add_f32 v[236:237], v[236:237], v[220:221]
	v_cvt_pk_bf16_f32 v216, v220, v221
	s_waitcnt lgkmcnt(6)
	v_mfma_f32_32x32x16_bf16 v[64:79], v[192:195], v[104:107], v[64:79]
	v_sub_f32_e32 v222, v222, v149
	v_sub_f32_e32 v223, v223, v149
	v_exp_f32_e32 v222, v222
	v_exp_f32_e32 v223, v223
	s_nop 0
	v_pk_add_f32 v[236:237], v[236:237], v[222:223]
	v_cvt_pk_bf16_f32 v217, v222, v223
	s_waitcnt lgkmcnt(5)
	v_mfma_f32_32x32x16_bf16 v[64:79], v[228:231], v[100:103], v[64:79]
	v_sub_f32_e32 v224, v224, v149
	v_sub_f32_e32 v225, v225, v149
	v_exp_f32_e32 v224, v224
	v_exp_f32_e32 v225, v225
	s_nop 0
	v_pk_add_f32 v[236:237], v[236:237], v[224:225]
	v_cvt_pk_bf16_f32 v218, v224, v225
	s_waitcnt lgkmcnt(4)
	v_mfma_f32_32x32x16_bf16 v[64:79], v[232:235], v[96:99], v[64:79]
	ds_read_b128 v[188:191], v147 offset:39424
	ds_read_b128 v[192:195], v147 offset:39456
	ds_read_b128 v[228:231], v147 offset:39488
	ds_read_b128 v[232:235], v147 offset:39520
	v_sub_f32_e32 v226, v226, v149
	v_sub_f32_e32 v227, v227, v149
	v_exp_f32_e32 v226, v226
	v_exp_f32_e32 v227, v227
	s_nop 0
	v_pk_add_f32 v[236:237], v[236:237], v[226:227]
	v_cvt_pk_bf16_f32 v219, v226, v227
	v_add_f32_e32 v128, v128, v236
	v_add_f32_e32 v128, v128, v237
	s_waitcnt lgkmcnt(7)
	v_mfma_f32_32x32x16_bf16 v[48:63], v[172:175], v[196:199], v[48:63]
	s_waitcnt lgkmcnt(6)
	v_mfma_f32_32x32x16_bf16 v[48:63], v[176:179], v[200:203], v[48:63]
	v_max3_f32 v145, v80, v81, v82
	v_max3_f32 v237, v64, v65, v66
	v_max3_f32 v145, v145, v83, v84
	s_waitcnt lgkmcnt(5)
	v_mfma_f32_32x32x16_bf16 v[48:63], v[180:183], v[212:215], v[48:63]
	v_max3_f32 v237, v237, v67, v68
	v_max3_f32 v145, v145, v85, v86
	v_max3_f32 v237, v237, v69, v70
	s_waitcnt lgkmcnt(4)
	v_mfma_f32_32x32x16_bf16 v[48:63], v[184:187], v[216:219], v[48:63]
	v_max3_f32 v145, v145, v87, v88
	v_max3_f32 v237, v237, v71, v72
	v_max3_f32 v145, v145, v89, v90
	ds_read_b128 v[172:175], v147 offset:44032
	ds_read_b128 v[176:179], v147 offset:44064
	ds_read_b128 v[180:183], v147 offset:44096
	ds_read_b128 v[184:187], v147 offset:44128
	s_waitcnt lgkmcnt(7)
	v_mfma_f32_32x32x16_bf16 v[32:47], v[188:191], v[196:199], v[32:47]
	v_max3_f32 v237, v237, v73, v74
	v_max3_f32 v145, v145, v91, v92
	v_max3_f32 v237, v237, v75, v76
	s_waitcnt lgkmcnt(6)
	v_mfma_f32_32x32x16_bf16 v[32:47], v[192:195], v[200:203], v[32:47]
	v_max3_f32 v145, v145, v93, v94
	v_max3_f32 v237, v237, v77, v78
	v_max_f32_e32 v145, v145, v95
	s_waitcnt lgkmcnt(5)
	v_mfma_f32_32x32x16_bf16 v[32:47], v[228:231], v[212:215], v[32:47]
	v_max_f32_e32 v237, v237, v79
	v_max_f32_e32 v145, v145, v237
	ds_bpermute_b32 v237, v158, v145
	s_waitcnt lgkmcnt(5)
	v_mfma_f32_32x32x16_bf16 v[32:47], v[232:235], v[216:219], v[32:47]
	v_add_u32_e32 v239, v131, v164
	s_waitcnt vmcnt(3)
	ds_write_b128 v239, v[116:119] offset:17408
	ds_read_b128 v[188:191], v147 offset:48640
	ds_read_b128 v[192:195], v147 offset:48672
	ds_read_b128 v[228:231], v147 offset:48704
	ds_read_b128 v[232:235], v147 offset:48736
	s_waitcnt lgkmcnt(9)
	v_mfma_f32_32x32x16_bf16 v[16:31], v[172:175], v[196:199], v[16:31]
	v_add_u32_e32 v239, v131, v165
	s_waitcnt vmcnt(2)
	ds_write_b128 v239, v[112:115] offset:17408
	s_waitcnt lgkmcnt(9)
	v_mfma_f32_32x32x16_bf16 v[16:31], v[176:179], v[200:203], v[16:31]
	v_add_u32_e32 v239, v156, v166
	s_waitcnt vmcnt(1)
	ds_write_b128 v239, v[124:127] offset:34816
	s_waitcnt lgkmcnt(9)
	v_mfma_f32_32x32x16_bf16 v[16:31], v[180:183], v[212:215], v[16:31]
	v_add_u32_e32 v239, v156, v167
	s_waitcnt vmcnt(0)
	ds_write_b128 v239, v[120:123] offset:34816
	s_waitcnt lgkmcnt(9)
	v_mfma_f32_32x32x16_bf16 v[16:31], v[184:187], v[216:219], v[16:31]
	s_waitcnt lgkmcnt(8)
	v_max_f32_e32 v237, v145, v237
	v_add_f32_e32 v239, 0x41000000, v149
	v_max_f32_e32 v145, v149, v237
	v_sub_f32_e32 v238, v149, v145
	v_cmp_gt_f32_e32 vcc, v237, v239
	v_exp_f32_e32 v238, v238
	s_cbranch_vccz .Lat_keepm_5
	v_mov_b32_e32 v149, v145

; __device__ __forceinline__ unsigned cvt_pk_bf16(float lo, float hi) { unsigned r; asm volatile("v_cvt_pk_bf16_f32 %0, %1, %2" : "=v"(r) : "v"(lo), "v"(hi)); return r; }
; #define AT_LDV(set, vb) do { _Pragma("unroll") for (int kb = 0; kb < 2; ++kb) _Pragma("unroll") for (int s2 = 0; s2 < 2; ++s2) \
;                     vf[set][kb * 2 + s2] = *(const bf16x8*)(sVt + buf * 9216 + (32 * (vb) + ql) * 72 + 32 * kb + 16 * s2 + 8 * g); } while (0)
; __device__ __forceinline__ void phase_attn(const Params& p, unsigned char* lds) {
;     ...
;             AT_QK(st, buf);
;             float mloc = st[0][0];
; #pragma unroll
;             for (int i = 0; i < 16; ++i) { mloc = fmaxf(mloc, st[0][i]); mloc = fmaxf(mloc, st[1][i]); }
;             mloc = fmaxf(mloc, __shfl_xor(mloc, 32));
;             const float mnew = fmaxf(mrun, mloc);
;             if (__builtin_amdgcn_ballot_w64(mnew > mrun) != 0ull) {
;                 const float alpha = __builtin_amdgcn_exp2f(mrun - mnew);
;                 lsum *= alpha;
; #pragma unroll
;                 for (int vb = 0; vb < 4; ++vb)
; #pragma unroll
;                     for (int i = 0; i < 16; ++i) ot[vb][i] *= alpha;
;             }
;             mrun = mnew;
;             bf16x8 P[2][2];
; #pragma unroll
;             for (int kb = 0; kb < 2; ++kb)
; #pragma unroll
;                 for (int s2 = 0; s2 < 2; ++s2) { u32x4 pk;
; #pragma unroll
;                     for (int jj = 0; jj < 4; ++jj) { const float p0 = __builtin_amdgcn_exp2f(st[kb][8 * s2 + 2 * jj] - mnew), p1 = __builtin_amdgcn_exp2f(st[kb][8 * s2 + 2 * jj + 1] - mnew); lsum += p0 + p1; pk[jj] = cvt_pk_bf16(p0, p1); }
;                     P[kb][s2] = __builtin_bit_cast(bf16x8, pk); }
;             {
;                 bf16x8 vf[2][4];
;     ...
;                 AT_LDV(0, 0);
; #pragma unroll
;                 for (int vb = 0; vb < 4; ++vb) {
;                     if (vb < 3) AT_LDV((vb + 1) & 1, vb + 1);
;                     __builtin_amdgcn_sched_barrier(0);
;                     __builtin_amdgcn_s_setprio(2);
; #pragma unroll
;                     for (int kb = 0; kb < 2; ++kb)
; #pragma unroll
;                         for (int s2 = 0; s2 < 2; ++s2) ot[vb] = __builtin_amdgcn_mfma_f32_32x32x16_bf16(vf[vb & 1][kb * 2 + s2], P[kb][s2], ot[vb], 0, 0, 0);
.Lat_norescale_6:
	v_mov_b32_e32 v236, 0
	v_mov_b32_e32 v237, 0
	v_mfma_f32_32x32x16_bf16 v[0:15], v[188:191], v[196:199], v[0:15]
	v_sub_f32_e32 v80, v80, v149
	v_sub_f32_e32 v81, v81, v149
	v_sub_f32_e32 v82, v82, v149
	v_sub_f32_e32 v83, v83, v149
	v_exp_f32_e32 v80, v80
	v_exp_f32_e32 v81, v81
	v_exp_f32_e32 v82, v82
	v_exp_f32_e32 v83, v83
	v_pk_add_f32 v[236:237], v[236:237], v[80:81]
	v_cvt_pk_bf16_f32 v80, v80, v81
	v_pk_add_f32 v[236:237], v[236:237], v[82:83]
	v_cvt_pk_bf16_f32 v81, v82, v83
	v_mfma_f32_32x32x16_bf16 v[0:15], v[192:195], v[200:203], v[0:15]
	v_sub_f32_e32 v84, v84, v149
	v_sub_f32_e32 v85, v85, v149
	v_sub_f32_e32 v86, v86, v149
	v_sub_f32_e32 v87, v87, v149
	v_exp_f32_e32 v84, v84
	v_exp_f32_e32 v85, v85
	v_exp_f32_e32 v86, v86
	v_exp_f32_e32 v87, v87
	v_pk_add_f32 v[236:237], v[236:237], v[84:85]
	v_cvt_pk_bf16_f32 v82, v84, v85
	v_pk_add_f32 v[236:237], v[236:237], v[86:87]
	v_cvt_pk_bf16_f32 v83, v86, v87
	v_mfma_f32_32x32x16_bf16 v[0:15], v[228:231], v[212:215], v[0:15]
	v_sub_f32_e32 v88, v88, v149
	v_sub_f32_e32 v89, v89, v149
	v_sub_f32_e32 v90, v90, v149
	v_sub_f32_e32 v91, v91, v149
	v_exp_f32_e32 v88, v88
	v_exp_f32_e32 v89, v89
	v_exp_f32_e32 v90, v90
	v_exp_f32_e32 v91, v91
	v_pk_add_f32 v[236:237], v[236:237], v[88:89]
	v_cvt_pk_bf16_f32 v84, v88, v89
	v_pk_add_f32 v[236:237], v[236:237], v[90:91]
	v_cvt_pk_bf16_f32 v85, v90, v91
	v_mfma_f32_32x32x16_bf16 v[0:15], v[232:235], v[216:219], v[0:15]
	ds_read_b128 v[188:191], v157 offset:26112
	ds_read_b128 v[192:195], v157 offset:26144
	ds_read_b128 v[228:231], v157 offset:26176
	ds_read_b128 v[232:235], v157 offset:26208
	v_sub_f32_e32 v92, v92, v149
	v_sub_f32_e32 v93, v93, v149
	v_sub_f32_e32 v94, v94, v149
	v_sub_f32_e32 v95, v95, v149
	v_exp_f32_e32 v92, v92
	v_exp_f32_e32 v93, v93
	v_exp_f32_e32 v94, v94
	v_exp_f32_e32 v95, v95
	v_pk_add_f32 v[236:237], v[236:237], v[92:93]
	v_cvt_pk_bf16_f32 v86, v92, v93
	v_pk_add_f32 v[236:237], v[236:237], v[94:95]
	v_cvt_pk_bf16_f32 v87, v94, v95
	s_waitcnt lgkmcnt(7)
	v_mfma_f32_32x32x16_bf16 v[196:211], v[172:175], v[108:111], 0
	v_sub_f32_e32 v64, v64, v149
	v_sub_f32_e32 v65, v65, v149
	v_exp_f32_e32 v64, v64
	v_exp_f32_e32 v65, v65
	s_nop 0
	v_pk_add_f32 v[236:237], v[236:237], v[64:65]
	v_cvt_pk_bf16_f32 v64, v64, v65
	s_waitcnt lgkmcnt(6)
	v_mfma_f32_32x32x16_bf16 v[196:211], v[176:179], v[104:107], v[196:211]
	v_sub_f32_e32 v66, v66, v149
	v_sub_f32_e32 v67, v67, v149
	v_exp_f32_e32 v66, v66
	v_exp_f32_e32 v67, v67
	s_nop 0
	v_pk_add_f32 v[236:237], v[236:237], v[66:67]
	v_cvt_pk_bf16_f32 v65, v66, v67
	s_cbranch_vccz .Lat_norescale_7
	v_pk_mul_f32 v[14:15], v[14:15], v[238:239] op_sel_hi:[1,0]
	v_pk_mul_f32 v[12:13], v[12:13], v[238:239] op_sel_hi:[1,0]
	v_pk_mul_f32 v[10:11], v[10:11], v[238:239] op_sel_hi:[1,0]
	v_pk_mul_f32 v[8:9], v[8:9], v[238:239] op_sel_hi:[1,0]
	v_pk_mul_f32 v[6:7], v[6:7], v[238:239] op_sel_hi:[1,0]
	v_pk_mul_f32 v[4:5], v[4:5], v[238:239] op_sel_hi:[1,0]
	v_pk_mul_f32 v[2:3], v[2:3], v[238:239] op_sel_hi:[1,0]
	v_pk_mul_f32 v[0:1], v[0:1], v[238:239] op_sel_hi:[1,0]
; __device__ __forceinline__ unsigned cvt_pk_bf16(float lo, float hi) { unsigned r; asm volatile("v_cvt_pk_bf16_f32 %0, %1, %2" : "=v"(r) : "v"(lo), "v"(hi)); return r; }
; __device__ __forceinline__ void phase_attn(const Params& p, unsigned char* lds) {
;     ...
;             AT_QK(st, buf);
;             float mloc = st[0][0];
; #pragma unroll
;             for (int i = 0; i < 16; ++i) { mloc = fmaxf(mloc, st[0][i]); mloc = fmaxf(mloc, st[1][i]); }
;             mloc = fmaxf(mloc, __shfl_xor(mloc, 32));
;             const float mnew = fmaxf(mrun, mloc);
;             if (__builtin_amdgcn_ballot_w64(mnew > mrun) != 0ull) {
;                 const float alpha = __builtin_amdgcn_exp2f(mrun - mnew);
;                 lsum *= alpha;
; #pragma unroll
;                 for (int vb = 0; vb < 4; ++vb)
; #pragma unroll
;                     for (int i = 0; i < 16; ++i) ot[vb][i] *= alpha;
;             }
;             mrun = mnew;
;             bf16x8 P[2][2];
; #pragma unroll
;             for (int kb = 0; kb < 2; ++kb)
; #pragma unroll
;                 for (int s2 = 0; s2 < 2; ++s2) { u32x4 pk;
; #pragma unroll
;                     for (int jj = 0; jj < 4; ++jj) { const float p0 = __builtin_amdgcn_exp2f(st[kb][8 * s2 + 2 * jj] - mnew), p1 = __builtin_amdgcn_exp2f(st[kb][8 * s2 + 2 * jj + 1] - mnew); lsum += p0 + p1; pk[jj] = cvt_pk_bf16(p0, p1); }
;                     P[kb][s2] = __builtin_bit_cast(bf16x8, pk); }
;             {
;                 bf16x8 vf[2][4];
;     ...
;                 AT_LDV(0, 0);
; #pragma unroll
;                 for (int vb = 0; vb < 4; ++vb) {
;                     if (vb < 3) AT_LDV((vb + 1) & 1, vb + 1);
;                     __builtin_amdgcn_sched_barrier(0);
;                     __builtin_amdgcn_s_setprio(2);
; #pragma unroll
;                     for (int kb = 0; kb < 2; ++kb)
; #pragma unroll
;                         for (int s2 = 0; s2 < 2; ++s2) ot[vb] = __builtin_amdgcn_mfma_f32_32x32x16_bf16(vf[vb & 1][kb * 2 + s2], P[kb][s2], ot[vb], 0, 0, 0);
;                     __builtin_amdgcn_s_setprio(0);
;                     __builtin_amdgcn_sched_barrier(0);
;                 }
;     ...
;             }
;             if (kt + 1 < 64) { AT_STOREK(buf ^ 1); AT_STOREV(buf ^ 1); }
;             __syncthreads();
;         }
.Lat_norescale_7:
	s_waitcnt lgkmcnt(5)
	v_mfma_f32_32x32x16_bf16 v[196:211], v[180:183], v[100:103], v[196:211]
	v_sub_f32_e32 v68, v68, v149
	v_sub_f32_e32 v69, v69, v149
	v_exp_f32_e32 v68, v68
	v_exp_f32_e32 v69, v69
	s_nop 0
	v_pk_add_f32 v[236:237], v[236:237], v[68:69]
	v_cvt_pk_bf16_f32 v66, v68, v69
	s_waitcnt lgkmcnt(4)
	v_mfma_f32_32x32x16_bf16 v[196:211], v[184:187], v[96:99], v[196:211]
	ds_read_b128 v[172:175], v159 offset:34816
	ds_read_b128 v[176:179], v159 offset:34848
	ds_read_b128 v[180:183], v159 offset:34880
	ds_read_b128 v[184:187], v159 offset:34912
	v_sub_f32_e32 v70, v70, v149
	v_sub_f32_e32 v71, v71, v149
	v_exp_f32_e32 v70, v70
	v_exp_f32_e32 v71, v71
	s_nop 0
	v_pk_add_f32 v[236:237], v[236:237], v[70:71]
	v_cvt_pk_bf16_f32 v67, v70, v71
	s_waitcnt lgkmcnt(7)
	v_mfma_f32_32x32x16_bf16 v[212:227], v[188:191], v[108:111], 0
	v_sub_f32_e32 v72, v72, v149
	v_sub_f32_e32 v73, v73, v149
	v_exp_f32_e32 v72, v72
	v_exp_f32_e32 v73, v73
	s_nop 0
	v_pk_add_f32 v[236:237], v[236:237], v[72:73]
	v_cvt_pk_bf16_f32 v68, v72, v73
	s_waitcnt lgkmcnt(6)
	v_mfma_f32_32x32x16_bf16 v[212:227], v[192:195], v[104:107], v[212:227]
	v_sub_f32_e32 v74, v74, v149
	v_sub_f32_e32 v75, v75, v149
	v_exp_f32_e32 v74, v74
	v_exp_f32_e32 v75, v75
	s_nop 0
	v_pk_add_f32 v[236:237], v[236:237], v[74:75]
	v_cvt_pk_bf16_f32 v69, v74, v75
	s_waitcnt lgkmcnt(5)
	v_mfma_f32_32x32x16_bf16 v[212:227], v[228:231], v[100:103], v[212:227]
	v_sub_f32_e32 v76, v76, v149
	v_sub_f32_e32 v77, v77, v149
	v_exp_f32_e32 v76, v76
	v_exp_f32_e32 v77, v77
	s_nop 0
	v_pk_add_f32 v[236:237], v[236:237], v[76:77]
	v_cvt_pk_bf16_f32 v70, v76, v77
	s_waitcnt lgkmcnt(4)
	v_mfma_f32_32x32x16_bf16 v[212:227], v[232:235], v[96:99], v[212:227]
	ds_read_b128 v[188:191], v159 offset:39424
	ds_read_b128 v[192:195], v159 offset:39456
	ds_read_b128 v[228:231], v159 offset:39488
	ds_read_b128 v[232:235], v159 offset:39520
	v_sub_f32_e32 v78, v78, v149
	v_sub_f32_e32 v79, v79, v149
	v_exp_f32_e32 v78, v78
	v_exp_f32_e32 v79, v79
	s_nop 0
	v_pk_add_f32 v[236:237], v[236:237], v[78:79]
	v_cvt_pk_bf16_f32 v71, v78, v79
	v_add_f32_e32 v128, v128, v236
	v_add_f32_e32 v128, v128, v237
	s_waitcnt lgkmcnt(7)
	v_mfma_f32_32x32x16_bf16 v[48:63], v[172:175], v[80:83], v[48:63]
	s_waitcnt lgkmcnt(6)
	v_mfma_f32_32x32x16_bf16 v[48:63], v[176:179], v[84:87], v[48:63]
	v_max3_f32 v145, v196, v197, v198
	v_max3_f32 v237, v212, v213, v214
	v_max3_f32 v145, v145, v199, v200
	s_waitcnt lgkmcnt(5)
	v_mfma_f32_32x32x16_bf16 v[48:63], v[180:183], v[64:67], v[48:63]
	v_max3_f32 v237, v237, v215, v216
	v_max3_f32 v145, v145, v201, v202
	v_max3_f32 v237, v237, v217, v218
	s_waitcnt lgkmcnt(4)
	v_mfma_f32_32x32x16_bf16 v[48:63], v[184:187], v[68:71], v[48:63]
	v_max3_f32 v145, v145, v203, v204
	v_max3_f32 v237, v237, v219, v220
	v_max3_f32 v145, v145, v205, v206
	ds_read_b128 v[172:175], v159 offset:44032
	ds_read_b128 v[176:179], v159 offset:44064
	ds_read_b128 v[180:183], v159 offset:44096
	ds_read_b128 v[184:187], v159 offset:44128
	s_waitcnt lgkmcnt(7)
	v_mfma_f32_32x32x16_bf16 v[32:47], v[188:191], v[80:83], v[32:47]
	v_max3_f32 v237, v237, v221, v222
	v_max3_f32 v145, v145, v207, v208
	v_max3_f32 v237, v237, v223, v224
	s_waitcnt lgkmcnt(6)
	v_mfma_f32_32x32x16_bf16 v[32:47], v[192:195], v[84:87], v[32:47]
	v_max3_f32 v145, v145, v209, v210
	v_max3_f32 v237, v237, v225, v226
	v_max_f32_e32 v145, v145, v211
	s_waitcnt lgkmcnt(5)
	v_mfma_f32_32x32x16_bf16 v[32:47], v[228:231], v[64:67], v[32:47]
	v_max_f32_e32 v237, v237, v227
	v_max_f32_e32 v145, v145, v237
	ds_bpermute_b32 v237, v158, v145
	s_waitcnt lgkmcnt(5)
	v_mfma_f32_32x32x16_bf16 v[32:47], v[232:235], v[68:71], v[32:47]
	v_add_u32_e32 v239, v131, v164
	s_waitcnt vmcnt(3)
	ds_write_b128 v239, v[116:119] offset:0
	ds_read_b128 v[188:191], v159 offset:48640
	ds_read_b128 v[192:195], v159 offset:48672
	ds_read_b128 v[228:231], v159 offset:48704
	ds_read_b128 v[232:235], v159 offset:48736
	s_waitcnt lgkmcnt(9)
	v_mfma_f32_32x32x16_bf16 v[16:31], v[172:175], v[80:83], v[16:31]
	v_add_u32_e32 v239, v131, v165
	s_waitcnt vmcnt(2)
	ds_write_b128 v239, v[112:115] offset:0
	s_waitcnt lgkmcnt(9)
	v_mfma_f32_32x32x16_bf16 v[16:31], v[176:179], v[84:87], v[16:31]
	v_add_u32_e32 v239, v156, v166
	s_waitcnt vmcnt(1)
	ds_write_b128 v239, v[124:127] offset:53248
	s_waitcnt lgkmcnt(9)
	v_mfma_f32_32x32x16_bf16 v[16:31], v[180:183], v[64:67], v[16:31]
	v_add_u32_e32 v239, v156, v167
	s_waitcnt vmcnt(0)
	ds_write_b128 v239, v[120:123] offset:53248
	s_waitcnt lgkmcnt(9)
	v_mfma_f32_32x32x16_bf16 v[16:31], v[184:187], v[68:71], v[16:31]
	s_waitcnt lgkmcnt(8)
	v_max_f32_e32 v237, v145, v237
	v_add_f32_e32 v239, 0x41000000, v149
	v_max_f32_e32 v145, v149, v237
	v_sub_f32_e32 v238, v149, v145
	v_cmp_gt_f32_e32 vcc, v237, v239
	v_exp_f32_e32 v238, v238
	s_cbranch_vccz .Lat_keepm_8
	v_mov_b32_e32 v149, v145

; __device__ __forceinline__ unsigned cvt_pk_bf16(float lo, float hi) { unsigned r; asm volatile("v_cvt_pk_bf16_f32 %0, %1, %2" : "=v"(r) : "v"(lo), "v"(hi)); return r; }
; __device__ __forceinline__ void phase_attn(const Params& p, unsigned char* lds) {
;     ...
;             const float mnew = fmaxf(mrun, mloc);
;             if (__builtin_amdgcn_ballot_w64(mnew > mrun) != 0ull) {
;                 const float alpha = __builtin_amdgcn_exp2f(mrun - mnew);
;                 lsum *= alpha;
; #pragma unroll
;                 for (int vb = 0; vb < 4; ++vb)
; #pragma unroll
;                     for (int i = 0; i < 16; ++i) ot[vb][i] *= alpha;
;             }
;             mrun = mnew;
;             bf16x8 P[2][2];
; #pragma unroll
;             for (int kb = 0; kb < 2; ++kb)
; #pragma unroll
;                 for (int s2 = 0; s2 < 2; ++s2) { u32x4 pk;
; #pragma unroll
;                     for (int jj = 0; jj < 4; ++jj) { const float p0 = __builtin_amdgcn_exp2f(st[kb][8 * s2 + 2 * jj] - mnew), p1 = __builtin_amdgcn_exp2f(st[kb][8 * s2 + 2 * jj + 1] - mnew); lsum += p0 + p1; pk[jj] = cvt_pk_bf16(p0, p1); }
;                     P[kb][s2] = __builtin_bit_cast(bf16x8, pk); }
.Lat_norescale_9:
	v_mov_b32_e32 v236, 0
	v_mov_b32_e32 v237, 0
	v_mfma_f32_32x32x16_bf16 v[0:15], v[188:191], v[80:83], v[0:15]
	v_sub_f32_e32 v196, v196, v149
	v_sub_f32_e32 v197, v197, v149
	v_sub_f32_e32 v198, v198, v149
	v_sub_f32_e32 v199, v199, v149
	v_sub_f32_e32 v200, v200, v149
	v_sub_f32_e32 v201, v201, v149
	v_sub_f32_e32 v202, v202, v149
	v_sub_f32_e32 v203, v203, v149
	v_exp_f32_e32 v196, v196
	v_exp_f32_e32 v197, v197
	v_exp_f32_e32 v198, v198
	v_exp_f32_e32 v199, v199
	v_exp_f32_e32 v200, v200
	v_exp_f32_e32 v201, v201
	v_exp_f32_e32 v202, v202
	v_exp_f32_e32 v203, v203
	v_pk_add_f32 v[236:237], v[236:237], v[196:197]
	v_cvt_pk_bf16_f32 v196, v196, v197
	v_pk_add_f32 v[236:237], v[236:237], v[198:199]
	v_cvt_pk_bf16_f32 v197, v198, v199
	v_pk_add_f32 v[236:237], v[236:237], v[200:201]
	v_cvt_pk_bf16_f32 v198, v200, v201
	v_pk_add_f32 v[236:237], v[236:237], v[202:203]
	v_cvt_pk_bf16_f32 v199, v202, v203
	v_mfma_f32_32x32x16_bf16 v[0:15], v[192:195], v[84:87], v[0:15]
	v_sub_f32_e32 v204, v204, v149
	v_sub_f32_e32 v205, v205, v149
	v_sub_f32_e32 v206, v206, v149
	v_sub_f32_e32 v207, v207, v149
	v_sub_f32_e32 v208, v208, v149
	v_sub_f32_e32 v209, v209, v149
	v_sub_f32_e32 v210, v210, v149
	v_sub_f32_e32 v211, v211, v149
	v_exp_f32_e32 v204, v204
	v_exp_f32_e32 v205, v205
	v_exp_f32_e32 v206, v206
	v_exp_f32_e32 v207, v207
	v_exp_f32_e32 v208, v208
	v_exp_f32_e32 v209, v209
	v_exp_f32_e32 v210, v210
	v_exp_f32_e32 v211, v211
	v_pk_add_f32 v[236:237], v[236:237], v[204:205]
	v_cvt_pk_bf16_f32 v200, v204, v205
	v_pk_add_f32 v[236:237], v[236:237], v[206:207]
	v_cvt_pk_bf16_f32 v201, v206, v207
	v_pk_add_f32 v[236:237], v[236:237], v[208:209]
	v_cvt_pk_bf16_f32 v202, v208, v209
	v_pk_add_f32 v[236:237], v[236:237], v[210:211]
	v_cvt_pk_bf16_f32 v203, v210, v211
	v_mfma_f32_32x32x16_bf16 v[0:15], v[228:231], v[64:67], v[0:15]
	v_sub_f32_e32 v212, v212, v149
	v_sub_f32_e32 v213, v213, v149
	v_sub_f32_e32 v214, v214, v149
	v_sub_f32_e32 v215, v215, v149
	v_sub_f32_e32 v216, v216, v149
	v_sub_f32_e32 v217, v217, v149
	v_sub_f32_e32 v218, v218, v149
	v_sub_f32_e32 v219, v219, v149
	v_exp_f32_e32 v212, v212
	v_exp_f32_e32 v213, v213
	v_exp_f32_e32 v214, v214
	v_exp_f32_e32 v215, v215
	v_exp_f32_e32 v216, v216
	v_exp_f32_e32 v217, v217
	v_exp_f32_e32 v218, v218
	v_exp_f32_e32 v219, v219
	v_pk_add_f32 v[236:237], v[236:237], v[212:213]
	v_cvt_pk_bf16_f32 v212, v212, v213
	v_pk_add_f32 v[236:237], v[236:237], v[214:215]
	v_cvt_pk_bf16_f32 v213, v214, v215
	v_pk_add_f32 v[236:237], v[236:237], v[216:217]
	v_cvt_pk_bf16_f32 v214, v216, v217
	v_pk_add_f32 v[236:237], v[236:237], v[218:219]
	v_cvt_pk_bf16_f32 v215, v218, v219
	v_mfma_f32_32x32x16_bf16 v[0:15], v[232:235], v[68:71], v[0:15]
	v_sub_f32_e32 v220, v220, v149
	v_sub_f32_e32 v221, v221, v149
	v_sub_f32_e32 v222, v222, v149
	v_sub_f32_e32 v223, v223, v149
	v_sub_f32_e32 v224, v224, v149
	v_sub_f32_e32 v225, v225, v149
	v_sub_f32_e32 v226, v226, v149
	v_sub_f32_e32 v227, v227, v149
	v_exp_f32_e32 v220, v220
	v_exp_f32_e32 v221, v221
	v_exp_f32_e32 v222, v222
	v_exp_f32_e32 v223, v223
	v_exp_f32_e32 v224, v224
	v_exp_f32_e32 v225, v225
	v_exp_f32_e32 v226, v226
	v_exp_f32_e32 v227, v227
	v_pk_add_f32 v[236:237], v[236:237], v[220:221]
	v_cvt_pk_bf16_f32 v216, v220, v221
	v_pk_add_f32 v[236:237], v[236:237], v[222:223]
	v_cvt_pk_bf16_f32 v217, v222, v223
	v_pk_add_f32 v[236:237], v[236:237], v[224:225]
	v_cvt_pk_bf16_f32 v218, v224, v225
	v_pk_add_f32 v[236:237], v[236:237], v[226:227]
	v_cvt_pk_bf16_f32 v219, v226, v227
	s_cbranch_vccz .Lat_norescale_10
	v_pk_mul_f32 v[14:15], v[14:15], v[238:239] op_sel_hi:[1,0]
	v_pk_mul_f32 v[12:13], v[12:13], v[238:239] op_sel_hi:[1,0]
	v_pk_mul_f32 v[10:11], v[10:11], v[238:239] op_sel_hi:[1,0]
	v_pk_mul_f32 v[8:9], v[8:9], v[238:239] op_sel_hi:[1,0]
	v_pk_mul_f32 v[6:7], v[6:7], v[238:239] op_sel_hi:[1,0]
	v_pk_mul_f32 v[4:5], v[4:5], v[238:239] op_sel_hi:[1,0]
	v_pk_mul_f32 v[2:3], v[2:3], v[238:239] op_sel_hi:[1,0]
	v_pk_mul_f32 v[0:1], v[0:1], v[238:239] op_sel_hi:[1,0]
; #define AT_STOREK(buf) do { _Pragma("unroll") for (int i_ = 0; i_ < 2; ++i_) { const int id_ = tid + 512 * i_; \
;             *(u32x4*)(sKt + (buf) * 8704 + (id_ >> 4) * 136 + (id_ & 15) * 8) = kr[i_]; } } while (0)
; #define AT_STOREV(buf) do { _Pragma("unroll") for (int i_ = 0; i_ < 2; ++i_) { const int id_ = tid + 512 * i_; \
;             *(u32x4*)(sVt + (buf) * 9216 + (id_ >> 3) * 72 + (id_ & 7) * 8) = vr[i_]; } } while (0)
; #define AT_LDV(set, vb) do { _Pragma("unroll") for (int kb = 0; kb < 2; ++kb) _Pragma("unroll") for (int s2 = 0; s2 < 2; ++s2) \
;                     vf[set][kb * 2 + s2] = *(const bf16x8*)(sVt + buf * 9216 + (32 * (vb) + ql) * 72 + 32 * kb + 16 * s2 + 8 * g); } while (0)
; __device__ __forceinline__ void phase_attn(const Params& p, unsigned char* lds) {
;     ...
;             {
;                 bf16x8 vf[2][4];
;     ...
;                 AT_LDV(0, 0);
; #pragma unroll
;                 for (int vb = 0; vb < 4; ++vb) {
;                     if (vb < 3) AT_LDV((vb + 1) & 1, vb + 1);
;                     __builtin_amdgcn_sched_barrier(0);
;                     __builtin_amdgcn_s_setprio(2);
; #pragma unroll
;                     for (int kb = 0; kb < 2; ++kb)
; #pragma unroll
;                         for (int s2 = 0; s2 < 2; ++s2) ot[vb] = __builtin_amdgcn_mfma_f32_32x32x16_bf16(vf[vb & 1][kb * 2 + s2], P[kb][s2], ot[vb], 0, 0, 0);
;                     __builtin_amdgcn_s_setprio(0);
;                     __builtin_amdgcn_sched_barrier(0);
;                 }
;     ...
;             }
;             if (kt + 1 < 64) { AT_STOREK(buf ^ 1); AT_STOREV(buf ^ 1); }
;             __syncthreads();
;         }
;     ...
;         lsum += __shfl_xor(lsum, 32);
;         const float inv = 1.0f / lsum;
;         if (cmap == 1) {
; #pragma unroll
;             for (int vb = 0; vb < 4; ++vb)
; #pragma unroll
;                 for (int i = 0; i < 16; ++i) ex[(vb * 16 + i) * 256 + qsub * 64 + lane] = ot[vb][i] * inv;
;         }
.Lat_norescale_10:
	ds_read_b128 v[172:175], v147 offset:34816
	ds_read_b128 v[176:179], v147 offset:34848
	ds_read_b128 v[180:183], v147 offset:34880
	ds_read_b128 v[184:187], v147 offset:34912
	ds_read_b128 v[188:191], v147 offset:39424
	ds_read_b128 v[192:195], v147 offset:39456
	ds_read_b128 v[228:231], v147 offset:39488
	ds_read_b128 v[232:235], v147 offset:39520
	v_add_f32_e32 v128, v128, v236
	v_add_f32_e32 v128, v128, v237
	s_waitcnt lgkmcnt(7)
	v_mfma_f32_32x32x16_bf16 v[48:63], v[172:175], v[196:199], v[48:63]
	s_waitcnt lgkmcnt(6)
	v_mfma_f32_32x32x16_bf16 v[48:63], v[176:179], v[200:203], v[48:63]
	s_waitcnt lgkmcnt(5)
	v_mfma_f32_32x32x16_bf16 v[48:63], v[180:183], v[212:215], v[48:63]
	s_waitcnt lgkmcnt(4)
	v_mfma_f32_32x32x16_bf16 v[48:63], v[184:187], v[216:219], v[48:63]
	ds_read_b128 v[172:175], v147 offset:44032
	ds_read_b128 v[176:179], v147 offset:44064
	ds_read_b128 v[180:183], v147 offset:44096
	ds_read_b128 v[184:187], v147 offset:44128
	s_waitcnt lgkmcnt(7)
	v_mfma_f32_32x32x16_bf16 v[32:47], v[188:191], v[196:199], v[32:47]
	s_waitcnt lgkmcnt(6)
	v_mfma_f32_32x32x16_bf16 v[32:47], v[192:195], v[200:203], v[32:47]
	s_waitcnt lgkmcnt(5)
	v_mfma_f32_32x32x16_bf16 v[32:47], v[228:231], v[212:215], v[32:47]
	s_waitcnt lgkmcnt(4)
	v_mfma_f32_32x32x16_bf16 v[32:47], v[232:235], v[216:219], v[32:47]
	ds_read_b128 v[188:191], v147 offset:48640
	ds_read_b128 v[192:195], v147 offset:48672
	ds_read_b128 v[228:231], v147 offset:48704
	ds_read_b128 v[232:235], v147 offset:48736
	s_waitcnt lgkmcnt(7)
	v_mfma_f32_32x32x16_bf16 v[16:31], v[172:175], v[196:199], v[16:31]
	s_waitcnt lgkmcnt(6)
	v_mfma_f32_32x32x16_bf16 v[16:31], v[176:179], v[200:203], v[16:31]
	s_waitcnt lgkmcnt(5)
	v_mfma_f32_32x32x16_bf16 v[16:31], v[180:183], v[212:215], v[16:31]
	s_waitcnt lgkmcnt(4)
	v_mfma_f32_32x32x16_bf16 v[16:31], v[184:187], v[216:219], v[16:31]
	s_waitcnt lgkmcnt(3)
	v_mfma_f32_32x32x16_bf16 v[0:15], v[188:191], v[196:199], v[0:15]
	s_waitcnt lgkmcnt(2)
	v_mfma_f32_32x32x16_bf16 v[0:15], v[192:195], v[200:203], v[0:15]
	s_waitcnt lgkmcnt(1)
	v_mfma_f32_32x32x16_bf16 v[0:15], v[228:231], v[212:215], v[0:15]
	s_waitcnt lgkmcnt(0)
	v_mfma_f32_32x32x16_bf16 v[0:15], v[232:235], v[216:219], v[0:15]
	v_mov_b32_e32 v64, v128
	ds_bpermute_b32 v65, v158, v64
	s_waitcnt lgkmcnt(0)
	s_barrier
	v_add_f32_e32 v64, v64, v65
	v_rcp_f32_e32 v66, v64
	s_nop 0
	v_fma_f32 v68, -v64, v66, 1.0
	v_fma_f32 v65, v68, v66, v66
	v_div_fixup_f32 v64, v65, v64, 1.0
	s_and_saveexec_b64 s[20:21], s[4:5]
	s_cbranch_execz .LBB0_2029
	v_mul_f32_e32 v65, v48, v64
	v_mul_f32_e32 v66, v49, v64
	ds_write2st64_b32 v160, v65, v66 offset1:4
	v_mul_f32_e32 v65, v50, v64
	v_mul_f32_e32 v66, v51, v64
	ds_write2st64_b32 v160, v65, v66 offset0:8 offset1:12
	v_mul_f32_e32 v65, v52, v64
	v_mul_f32_e32 v66, v53, v64
	ds_write2st64_b32 v160, v65, v66 offset0:16 offset1:20
	v_mul_f32_e32 v65, v54, v64
	v_mul_f32_e32 v66, v55, v64
	ds_write2st64_b32 v160, v65, v66 offset0:24 offset1:28
	v_mul_f32_e32 v65, v56, v64
	v_mul_f32_e32 v66, v57, v64
	ds_write2st64_b32 v160, v65, v66 offset0:32 offset1:36
	v_mul_f32_e32 v65, v58, v64
	v_mul_f32_e32 v66, v59, v64
	ds_write2st64_b32 v160, v65, v66 offset0:40 offset1:44
	v_mul_f32_e32 v65, v60, v64
	v_mul_f32_e32 v66, v61, v64
	ds_write2st64_b32 v160, v65, v66 offset0:48 offset1:52
	v_mul_f32_e32 v65, v62, v64
	v_mul_f32_e32 v66, v63, v64
	ds_write2st64_b32 v160, v65, v66 offset0:56 offset1:60
	v_mul_f32_e32 v65, v32, v64
	v_mul_f32_e32 v66, v33, v64
	ds_write2st64_b32 v160, v65, v66 offset0:64 offset1:68
	v_mul_f32_e32 v65, v34, v64
	v_mul_f32_e32 v66, v35, v64
	ds_write2st64_b32 v160, v65, v66 offset0:72 offset1:76
	v_mul_f32_e32 v65, v36, v64
	v_mul_f32_e32 v66, v37, v64
	ds_write2st64_b32 v160, v65, v66 offset0:80 offset1:84
	v_mul_f32_e32 v65, v38, v64
	v_mul_f32_e32 v66, v39, v64
	ds_write2st64_b32 v160, v65, v66 offset0:88 offset1:92
	v_mul_f32_e32 v65, v40, v64
	v_mul_f32_e32 v66, v41, v64
	ds_write2st64_b32 v160, v65, v66 offset0:96 offset1:100
	v_mul_f32_e32 v65, v42, v64
	v_mul_f32_e32 v66, v43, v64
	ds_write2st64_b32 v160, v65, v66 offset0:104 offset1:108
	v_mul_f32_e32 v65, v44, v64
	v_mul_f32_e32 v66, v45, v64
	ds_write2st64_b32 v160, v65, v66 offset0:112 offset1:116
	v_mul_f32_e32 v65, v46, v64
	v_mul_f32_e32 v66, v47, v64
	ds_write2st64_b32 v160, v65, v66 offset0:120 offset1:124
	v_mul_f32_e32 v65, v16, v64
	v_mul_f32_e32 v66, v17, v64
	ds_write2st64_b32 v160, v65, v66 offset0:128 offset1:132
	v_mul_f32_e32 v65, v18, v64
	v_mul_f32_e32 v66, v19, v64
	ds_write2st64_b32 v160, v65, v66 offset0:136 offset1:140
	v_mul_f32_e32 v65, v20, v64
	v_mul_f32_e32 v66, v21, v64
	ds_write2st64_b32 v160, v65, v66 offset0:144 offset1:148
	v_mul_f32_e32 v65, v22, v64
	v_mul_f32_e32 v66, v23, v64
	ds_write2st64_b32 v160, v65, v66 offset0:152 offset1:156
	v_mul_f32_e32 v65, v24, v64
	v_mul_f32_e32 v66, v25, v64
	ds_write2st64_b32 v160, v65, v66 offset0:160 offset1:164
	v_mul_f32_e32 v65, v26, v64
	v_mul_f32_e32 v66, v27, v64
	ds_write2st64_b32 v160, v65, v66 offset0:168 offset1:172
	v_mul_f32_e32 v65, v28, v64
	v_mul_f32_e32 v66, v29, v64
	ds_write2st64_b32 v160, v65, v66 offset0:176 offset1:180
	v_mul_f32_e32 v65, v30, v64
	v_mul_f32_e32 v66, v31, v64
	ds_write2st64_b32 v160, v65, v66 offset0:184 offset1:188
	v_mul_f32_e32 v65, v0, v64
	v_mul_f32_e32 v66, v1, v64
	ds_write2st64_b32 v160, v65, v66 offset0:192 offset1:196
	v_mul_f32_e32 v65, v2, v64
	v_mul_f32_e32 v66, v3, v64
	ds_write2st64_b32 v160, v65, v66 offset0:200 offset1:204
	v_mul_f32_e32 v65, v4, v64
	v_mul_f32_e32 v66, v5, v64
	ds_write2st64_b32 v160, v65, v66 offset0:208 offset1:212
	v_mul_f32_e32 v65, v6, v64
	v_mul_f32_e32 v66, v7, v64
	ds_write2st64_b32 v160, v65, v66 offset0:216 offset1:220
	v_mul_f32_e32 v65, v8, v64
	v_mul_f32_e32 v66, v9, v64
	ds_write2st64_b32 v160, v65, v66 offset0:224 offset1:228
	v_mul_f32_e32 v65, v10, v64
	v_mul_f32_e32 v66, v11, v64
	ds_write2st64_b32 v160, v65, v66 offset0:232 offset1:236
	v_mul_f32_e32 v65, v12, v64
	v_mul_f32_e32 v66, v13, v64
	ds_write2st64_b32 v160, v65, v66 offset0:240 offset1:244
	v_mul_f32_e32 v65, v14, v64
	v_mul_f32_e32 v66, v15, v64
	ds_write2st64_b32 v160, v65, v66 offset0:248 offset1:252
